# sgu_unit cross-unit pipelining: next unit's activation loads issued into spare registers during the current unit's compute
# baseline (speedup 1.0000x reference)
; __device__ __forceinline__ void sgu_unit(int chunk, int g, const bf16_t* ZUV, const float* SS2, const float* gn, const bf16_t* SGUW, const float* bs, bf16_t* MIX, LAS unsigned char* lds) {
;     ...
;     const int sr = tid & 127, qd = __builtin_amdgcn_readfirstlane(tid >> 7);
;     const bf16_t* zp = ZUV + (size_t)(r0 + sr) * 2048 + 1024 + g * 128 + qd * 32;
;     const bf16_t* wp = SGUW + (size_t)(g * 128 + t) * 128 + 8 * hi;
;     const bf16_t* zup = ZUV + (size_t)(r0 + t) * 2048 + g * 128;
;     u32x4 w[4]; f32x4 sq[4]; bf16x8 wvv[8]; u32x2 zav[4], zbv[4];
; #pragma unroll
;     for (int j = 0; j < 4; ++j) { w[j] = *(const u32x4*)(zp + j * 8); sq[j] = *(const f32x4*)(SS2 + (size_t)(r0 + sr) * 16 + 4 * j); }
; #pragma unroll
;     for (int ks = 0; ks < 8; ++ks) wvv[ks] = *(const bf16x8*)(wp + 16 * ks);
; #pragma unroll
;     for (int j = 0; j < 4; ++j) { zav[j] = *(const u32x2*)(zup + 32 * cb0 + 8 * j + 4 * hi); zbv[j] = *(const u32x2*)(zup + 32 * cb0 + 8 * j + 4 * hi + 32); }
;     const float bt = bs[g * 128 + t];
;     asm volatile("" : "+v"(w[0]), "+v"(w[1]), "+v"(w[2]), "+v"(w[3]), "+v"(sq[0]), "+v"(sq[1]), "+v"(sq[2]), "+v"(sq[3]),
;                  "+v"(wvv[0]), "+v"(wvv[1]), "+v"(wvv[2]), "+v"(wvv[3]), "+v"(wvv[4]), "+v"(wvv[5]), "+v"(wvv[6]), "+v"(wvv[7]),
;                  "+v"(zav[0]), "+v"(zav[1]), "+v"(zav[2]), "+v"(zav[3]), "+v"(zbv[0]), "+v"(zbv[1]), "+v"(zbv[2]), "+v"(zbv[3]) :: "memory");
.LBB0_249:
	v_mov_b32_e32 v0, v198
	v_mov_b32_e32 v2, s9
	v_readfirstlane_b32 s0, v0
	s_lshr_b32 s4, s0, 1
	v_and_b32_e32 v30, 31, v0
	s_and_b32 s4, s4, 0x60
	v_or_b32_e32 v6, s4, v30
	s_movk_i32 s4, 0x7f
	v_bfi_b32 v2, s4, v0, v2
	s_and_b32 s1, s9, 0xffffff80
	v_ashrrev_i32_e32 v3, 31, v2
	v_lshlrev_b64 v[4:5], 12, v[2:3]
	s_and_b32 s6, s8, 0x380
	s_ashr_i32 s0, s0, 2
	v_or_b32_e32 v80, s1, v6
	v_lshl_add_u64 v[4:5], s[54:55], 0, v[4:5]
	s_lshl_b32 s50, s6, 1
	s_and_b32 s4, s0, 0xffffffe0
	v_ashrrev_i32_e32 v81, 31, v80
	v_lshl_add_u64 v[4:5], v[4:5], 0, s[50:51]
	s_ashr_i32 s5, s4, 31
	v_or_b32_e32 v36, s6, v6
	v_lshlrev_b64 v[6:7], 12, v[80:81]
	v_lshl_add_u64 v[4:5], s[4:5], 1, v[4:5]
	v_lshl_add_u64 v[34:35], s[54:55], 0, v[6:7]
	v_lshlrev_b64 v[2:3], 6, v[2:3]
	s_andn2_b32 s0, s0, 63
	v_bfe_u32 v65, v0, 5, 1
	v_lshl_add_u64 v[2:3], s[16:17], 0, v[2:3]
	v_lshl_add_u64 v[238:239], v[4:5], 0, s[98:99]
	v_lshl_add_u64 v[240:241], v[2:3], 0, s[100:101]
	s_cmp_eq_u32 s10, s2
	s_cbranch_scc0 .Lsgu_mov1
	global_load_dwordx4 v[6:9], v[4:5], off offset:2096
	global_load_dwordx4 v[10:13], v[4:5], off offset:2080
	global_load_dwordx4 v[14:17], v[4:5], off offset:2064
	global_load_dwordx4 v[18:21], v[4:5], off offset:2048
	global_load_dwordx4 v[22:25], v[2:3], off offset:48
	global_load_dwordx4 v[26:29], v[2:3], off offset:32
	global_load_dwordx4 v[82:85], v[2:3], off offset:16
	global_load_dwordx4 v[86:89], v[2:3], off
	s_branch .Lsgu_j1
.Lsgu_mov1:
	s_waitcnt vmcnt(8)
	v_mov_b64_e32 v[6:7], v[166:167]
	v_mov_b64_e32 v[8:9], v[168:169]
	v_mov_b64_e32 v[10:11], v[170:171]
	v_mov_b64_e32 v[12:13], v[172:173]
	v_mov_b64_e32 v[14:15], v[174:175]
	v_mov_b64_e32 v[16:17], v[176:177]
	v_mov_b64_e32 v[18:19], v[178:179]
	v_mov_b64_e32 v[20:21], v[180:181]
	v_mov_b64_e32 v[22:23], v[182:183]
	v_mov_b64_e32 v[24:25], v[184:185]
	v_mov_b64_e32 v[26:27], v[186:187]
	v_mov_b64_e32 v[28:29], v[188:189]
	v_mov_b64_e32 v[82:83], v[190:191]
	v_mov_b64_e32 v[84:85], v[192:193]
	v_mov_b64_e32 v[86:87], v[194:195]
	v_mov_b64_e32 v[88:89], v[196:197]
.Lsgu_j1:
	v_lshl_add_u64 v[4:5], v[34:35], 0, s[50:51]
	s_ashr_i32 s1, s0, 31
	v_and_b32_e32 v31, 0x7f, v0
	v_lshlrev_b32_e32 v0, 8, v36
	v_lshlrev_b32_e32 v32, 3, v65
	v_mov_b32_e32 v33, v1
	v_lshl_add_u64 v[4:5], s[0:1], 1, v[4:5]
	v_lshl_add_u64 v[2:3], s[12:13], 0, v[0:1]
	v_lshlrev_b32_e32 v0, 4, v65
	v_lshl_add_u64 v[4:5], v[4:5], 0, v[32:33]
	v_lshl_add_u64 v[2:3], v[2:3], 0, v[0:1]
	v_lshl_add_u64 v[242:243], v[4:5], 0, s[98:99]
	s_cmp_eq_u32 s10, s2
	s_cbranch_scc0 .Lsgu_mov2
	global_load_dwordx2 v[78:79], v[4:5], off
	global_load_dwordx2 v[76:77], v[4:5], off offset:64
	global_load_dwordx2 v[74:75], v[4:5], off offset:16
	global_load_dwordx2 v[72:73], v[4:5], off offset:80
	global_load_dwordx2 v[70:71], v[4:5], off offset:32
	global_load_dwordx2 v[68:69], v[4:5], off offset:96
	global_load_dwordx2 v[66:67], v[4:5], off offset:48
	global_load_dwordx2 v[62:63], v[4:5], off offset:112
	s_branch .Lsgu_j2
.Lsgu_mov2:
	v_mov_b64_e32 v[78:79], v[244:245]
	v_mov_b64_e32 v[76:77], v[246:247]
	v_mov_b64_e32 v[74:75], v[248:249]
	v_mov_b64_e32 v[72:73], v[250:251]
	v_mov_b64_e32 v[70:71], v[124:125]
	v_mov_b64_e32 v[68:69], v[126:127]
	v_mov_b64_e32 v[66:67], v[128:129]
	v_mov_b64_e32 v[62:63], v[158:159]
.Lsgu_j2:
	v_lshlrev_b32_e32 v4, 2, v36
	global_load_dword v64, v4, s[22:23]
	global_load_dwordx4 v[34:37], v[2:3], off offset:224
	global_load_dwordx4 v[38:41], v[2:3], off offset:192
	global_load_dwordx4 v[42:45], v[2:3], off offset:160
	global_load_dwordx4 v[46:49], v[2:3], off offset:128
	global_load_dwordx4 v[50:53], v[2:3], off offset:96
	global_load_dwordx4 v[54:57], v[2:3], off offset:64
	global_load_dwordx4 v[58:61], v[2:3], off offset:32
	s_nop 0
	global_load_dwordx4 v[2:5], v[2:3], off
	s_lshl_b32 s1, s6, 2
	s_add_u32 s1, s14, s1
	s_addc_u32 s11, s15, 0
	s_lshl_b64 s[6:7], s[4:5], 2
	s_add_u32 s6, s1, s6
	s_addc_u32 s7, s11, s7
	s_mul_i32 s1, s4, 0x110
	s_add_i32 s1, s1, 0
	v_lshl_add_u32 v31, v31, 1, s1
	s_add_i32 s10, s10, s34
	s_add_i32 s9, s9, s96
	s_add_i32 s8, s8, s20
	s_cmpk_gt_i32 s10, 0xfff
	global_load_dwordx4 v[206:209], v1, s[6:7]
	global_load_dwordx4 v[210:213], v1, s[6:7] offset:16
	global_load_dwordx4 v[214:217], v1, s[6:7] offset:32
	global_load_dwordx4 v[218:221], v1, s[6:7] offset:48
	global_load_dwordx4 v[222:225], v1, s[6:7] offset:64
	global_load_dwordx4 v[226:229], v1, s[6:7] offset:80
	global_load_dwordx4 v[230:233], v1, s[6:7] offset:96
	global_load_dwordx4 v[234:237], v1, s[6:7] offset:112
	s_waitcnt vmcnt(0)
; #define LAS __attribute__((address_space(3)))
; __device__ __forceinline__ unsigned pk_bf16(float lo, float hi) { const f32x2_t v = {lo, hi}; const bf16x2_t b = __builtin_convertvector(v, bf16x2_t); return __builtin_bit_cast(unsigned, b); }
; __device__ __forceinline__ float bf_lo(unsigned w) { return __uint_as_float(w << 16); }
; __device__ __forceinline__ float bf_hi(unsigned w) { return __uint_as_float(w & 0xffff0000u); }
; __device__ __forceinline__ void sgu_unit(int chunk, int g, const bf16_t* ZUV, const float* SS2, const float* gn, const bf16_t* SGUW, const float* bs, bf16_t* MIX, LAS unsigned char* lds) {
;     ...
;     asm volatile("" : "+v"(w[0]), "+v"(w[1]), "+v"(w[2]), "+v"(w[3]), "+v"(sq[0]), "+v"(sq[1]), "+v"(sq[2]), "+v"(sq[3]),
;                  "+v"(wvv[0]), "+v"(wvv[1]), "+v"(wvv[2]), "+v"(wvv[3]), "+v"(wvv[4]), "+v"(wvv[5]), "+v"(wvv[6]), "+v"(wvv[7]),
;                  "+v"(zav[0]), "+v"(zav[1]), "+v"(zav[2]), "+v"(zav[3]), "+v"(zbv[0]), "+v"(zbv[1]), "+v"(zbv[2]), "+v"(zbv[3]) :: "memory");
;     {
;         const float sm = ((sq[0].x + sq[0].y) + (sq[0].z + sq[0].w)) + ((sq[1].x + sq[1].y) + (sq[1].z + sq[1].w)) + ((sq[2].x + sq[2].y) + (sq[2].z + sq[2].w)) + ((sq[3].x + sq[3].y) + (sq[3].z + sq[3].w));
;         const float rs = rsqrtf(sm * (1.0f / 1024.0f) + EPS);
; #pragma unroll
;         for (int j = 0; j < 4; ++j) {
;             const float* gp = gn + g * 128 + qd * 32 + j * 8; const f32x4 g0 = *(const f32x4*)gp, g1 = *(const f32x4*)(gp + 4);
;             const float v[8] = {bf_lo(w[j].x) * rs * g0.x, bf_hi(w[j].x) * rs * g0.y, bf_lo(w[j].y) * rs * g0.z, bf_hi(w[j].y) * rs * g0.w, bf_lo(w[j].z) * rs * g1.x, bf_hi(w[j].z) * rs * g1.y, bf_lo(w[j].w) * rs * g1.z, bf_hi(w[j].w) * rs * g1.w};
;             LAS bf16_t* zt = ZT + (qd * 32 + j * 8) * 136 + sr;
; #pragma unroll
;             for (int e = 0; e < 8; ++e) zt[e * 136] = (bf16_t)(pk_bf16(v[e], 0.f) & 0xffffu);
;         }
;     }
;     __syncthreads();
	global_load_dwordx4 v[166:169], v[238:239], off offset:2096
	global_load_dwordx4 v[170:173], v[238:239], off offset:2080
	global_load_dwordx4 v[174:177], v[238:239], off offset:2064
	global_load_dwordx4 v[178:181], v[238:239], off offset:2048
	global_load_dwordx4 v[182:185], v[240:241], off offset:48
	global_load_dwordx4 v[186:189], v[240:241], off offset:32
	global_load_dwordx4 v[190:193], v[240:241], off offset:16
	global_load_dwordx4 v[194:197], v[240:241], off
	global_load_dwordx2 v[244:245], v[242:243], off
	global_load_dwordx2 v[246:247], v[242:243], off offset:64
	global_load_dwordx2 v[248:249], v[242:243], off offset:16
	global_load_dwordx2 v[250:251], v[242:243], off offset:80
	global_load_dwordx2 v[124:125], v[242:243], off offset:32
	global_load_dwordx2 v[126:127], v[242:243], off offset:96
	global_load_dwordx2 v[128:129], v[242:243], off offset:48
	global_load_dwordx2 v[158:159], v[242:243], off offset:112
	s_nop 0
	v_mov_b32_e32 v32, v87
	v_mov_b32_e32 v33, v88
	v_mov_b32_e32 v87, v89
	v_pk_add_f32 v[32:33], v[32:33], v[86:87]
	v_mov_b32_e32 v86, v83
	v_mov_b32_e32 v87, v84
	v_mov_b32_e32 v83, v85
	v_pk_add_f32 v[82:83], v[86:87], v[82:83]
	v_pk_add_f32 v[32:33], v[32:33], v[32:33] op_sel_hi:[0,1]
	v_pk_add_f32 v[82:83], v[82:83], v[82:83] op_sel_hi:[0,1]
	v_add_f32_e32 v27, v26, v27
	v_add_f32_e32 v29, v28, v29
	v_mov_b32_e32 v26, v22
	v_mov_b32_e32 v28, v23
	v_mov_b32_e32 v32, v24
	v_mov_b32_e32 v82, v25
	v_pk_add_f32 v[22:23], v[26:27], v[28:29]
	v_pk_add_f32 v[24:25], v[32:33], v[82:83]
	v_lshlrev_b32_e32 v33, 16, v18
	v_pk_add_f32 v[22:23], v[22:23], v[24:25]
	v_and_b32_e32 v18, 0xffff0000, v18
	v_add_f32_e32 v22, v22, v23
	v_fmamk_f32 v22, v22, 0x3a800000, v201
	v_cmp_gt_f32_e32 vcc, s57, v22
	v_mul_f32_e32 v23, 0x4b800000, v22
	s_nop 0
	v_cndmask_b32_e32 v22, v22, v23, vcc
	v_rsq_f32_e32 v22, v22
	s_nop 0
	v_mul_f32_e32 v23, 0x45800000, v22
	v_cndmask_b32_e32 v32, v22, v23, vcc
	v_mul_f32_e32 v33, v32, v33
	v_mul_f32_e32 v18, v32, v18
	v_mul_f32_e32 v33, v206, v33
	v_lshlrev_b32_e32 v86, 16, v19
	v_mul_f32_e32 v18, v207, v18
	v_mul_f32_e32 v86, v32, v86
	v_and_b32_e32 v19, 0xffff0000, v19
	v_mul_f32_e32 v86, v208, v86
	v_mul_f32_e32 v19, v32, v19
	v_lshlrev_b32_e32 v87, 16, v20
	v_and_b32_e32 v20, 0xffff0000, v20
	v_cvt_pk_bf16_f32 v18, v18, s0
	v_mul_f32_e32 v19, v209, v19
	v_mul_f32_e32 v87, v32, v87
	v_mul_f32_e32 v20, v32, v20
	ds_write_b16 v31, v18 offset:272
	v_cvt_pk_bf16_f32 v18, v86, s0
	v_mul_f32_e32 v82, v210, v87
	v_mul_f32_e32 v20, v211, v20
	v_lshlrev_b32_e32 v83, 16, v21
	ds_write_b16 v31, v18 offset:544
	v_cvt_pk_bf16_f32 v18, v19, s0
	v_mul_f32_e32 v83, v32, v83
	v_and_b32_e32 v21, 0xffff0000, v21
	ds_write_b16 v31, v18 offset:816
	v_cvt_pk_bf16_f32 v18, v82, s0
	v_mul_f32_e32 v83, v212, v83
	v_mul_f32_e32 v21, v32, v21
	ds_write_b16 v31, v18 offset:1088
	v_cvt_pk_bf16_f32 v18, v20, s0
	v_mul_f32_e32 v21, v213, v21
	ds_write_b16 v31, v18 offset:1360
	v_cvt_pk_bf16_f32 v18, v83, s0
	ds_write_b16 v31, v18 offset:1632
	v_cvt_pk_bf16_f32 v18, v21, s0
	ds_write_b16 v31, v18 offset:1904
	v_lshlrev_b32_e32 v18, 16, v14
	v_and_b32_e32 v14, 0xffff0000, v14
	v_mul_f32_e32 v14, v32, v14
	v_lshlrev_b32_e32 v19, 16, v15
	v_mul_f32_e32 v14, v215, v14
	v_mul_f32_e32 v19, v32, v19
	v_and_b32_e32 v15, 0xffff0000, v15
	v_mul_f32_e32 v19, v216, v19
	v_mul_f32_e32 v15, v32, v15
	v_lshlrev_b32_e32 v20, 16, v16
	v_cvt_pk_bf16_f32 v14, v14, s0
	v_mul_f32_e32 v15, v217, v15
	v_mul_f32_e32 v20, v32, v20
	v_and_b32_e32 v16, 0xffff0000, v16
	ds_write_b16 v31, v14 offset:2448
	v_cvt_pk_bf16_f32 v14, v19, s0
	v_mul_f32_e32 v20, v218, v20
	v_mul_f32_e32 v16, v32, v16
	v_lshlrev_b32_e32 v21, 16, v17
	ds_write_b16 v31, v14 offset:2720
	v_cvt_pk_bf16_f32 v14, v15, s0
	v_mul_f32_e32 v16, v219, v16
	v_mul_f32_e32 v21, v32, v21
	v_and_b32_e32 v17, 0xffff0000, v17
	ds_write_b16 v31, v14 offset:2992
	v_cvt_pk_bf16_f32 v14, v20, s0
	v_mul_f32_e32 v18, v32, v18
	v_mul_f32_e32 v21, v220, v21
	v_mul_f32_e32 v17, v32, v17
	ds_write_b16 v31, v14 offset:3264
	v_cvt_pk_bf16_f32 v14, v16, s0
	v_mul_f32_e32 v18, v214, v18
	v_mul_f32_e32 v17, v221, v17
	ds_write_b16 v31, v14 offset:3536
	v_cvt_pk_bf16_f32 v14, v21, s0
	v_cvt_pk_bf16_f32 v33, v33, s0
	v_cvt_pk_bf16_f32 v18, v18, s0
	ds_write_b16 v31, v14 offset:3808
	v_cvt_pk_bf16_f32 v14, v17, s0
	ds_write_b16 v31, v33
	ds_write_b16 v31, v18 offset:2176
	ds_write_b16 v31, v14 offset:4080
	v_lshlrev_b32_e32 v33, 16, v10
	v_and_b32_e32 v10, 0xffff0000, v10
	v_mul_f32_e32 v10, v32, v10
	v_mul_f32_e32 v33, v32, v33
	v_mul_f32_e32 v10, v10, v223
	v_lshlrev_b32_e32 v27, 16, v11
	v_mul_f32_e32 v27, v32, v27
	v_and_b32_e32 v11, 0xffff0000, v11
	v_mul_f32_e32 v27, v27, v224
	v_mul_f32_e32 v11, v32, v11
	v_lshlrev_b32_e32 v28, 16, v12
	v_and_b32_e32 v12, 0xffff0000, v12
	v_cvt_pk_bf16_f32 v10, v10, s0
	v_mul_f32_e32 v11, v11, v225
	v_mul_f32_e32 v28, v32, v28
	v_mul_f32_e32 v12, v32, v12
	ds_write_b16 v31, v10 offset:4624
	v_cvt_pk_bf16_f32 v10, v27, s0
	v_mul_f32_e32 v22, v28, v226
	v_mul_f32_e32 v12, v12, v227
	v_lshlrev_b32_e32 v23, 16, v13
	ds_write_b16 v31, v10 offset:4896
	v_cvt_pk_bf16_f32 v10, v11, s0
	v_mul_f32_e32 v23, v32, v23
	v_and_b32_e32 v13, 0xffff0000, v13
	ds_write_b16 v31, v10 offset:5168
	v_cvt_pk_bf16_f32 v10, v22, s0
	v_mul_f32_e32 v23, v23, v228
	v_mul_f32_e32 v13, v32, v13
	ds_write_b16 v31, v10 offset:5440
	v_cvt_pk_bf16_f32 v10, v12, s0
	v_mul_f32_e32 v13, v13, v229
	ds_write_b16 v31, v10 offset:5712
	v_cvt_pk_bf16_f32 v10, v23, s0
	ds_write_b16 v31, v10 offset:5984
	v_cvt_pk_bf16_f32 v10, v13, s0
	ds_write_b16 v31, v10 offset:6256
	v_lshlrev_b32_e32 v10, 16, v6
	v_and_b32_e32 v6, 0xffff0000, v6
	v_mul_f32_e32 v6, v32, v6
	v_lshlrev_b32_e32 v11, 16, v7
	v_mul_f32_e32 v6, v6, v231
	v_mul_f32_e32 v11, v32, v11
	v_and_b32_e32 v7, 0xffff0000, v7
	v_mul_f32_e32 v11, v11, v232
	v_mul_f32_e32 v7, v32, v7
	v_lshlrev_b32_e32 v12, 16, v8
	v_cvt_pk_bf16_f32 v6, v6, s0
	v_mul_f32_e32 v7, v7, v233
	v_mul_f32_e32 v12, v32, v12
	v_and_b32_e32 v8, 0xffff0000, v8
	ds_write_b16 v31, v6 offset:6800
	v_cvt_pk_bf16_f32 v6, v11, s0
	v_mul_f32_e32 v12, v12, v234
	v_mul_f32_e32 v8, v32, v8
	v_lshlrev_b32_e32 v13, 16, v9
	ds_write_b16 v31, v6 offset:7072
	v_cvt_pk_bf16_f32 v6, v7, s0
	v_mul_f32_e32 v8, v8, v235
	v_mul_f32_e32 v13, v32, v13
	v_and_b32_e32 v9, 0xffff0000, v9
	ds_write_b16 v31, v6 offset:7344
	v_cvt_pk_bf16_f32 v6, v12, s0
	v_mul_f32_e32 v13, v13, v236
	v_mul_f32_e32 v9, v32, v9
	ds_write_b16 v31, v6 offset:7616
	v_cvt_pk_bf16_f32 v6, v8, s0
	v_mul_f32_e32 v9, v9, v237
	ds_write_b16 v31, v6 offset:7888
	v_cvt_pk_bf16_f32 v6, v13, s0
	ds_write_b16 v31, v6 offset:8160
	v_cvt_pk_bf16_f32 v6, v9, s0
	v_mul_f32_e32 v10, v32, v10
	ds_write_b16 v31, v6 offset:8432
	v_or_b32_e32 v6, s0, v30
	v_mul_f32_e32 v26, v33, v222
	v_mul_f32_e32 v10, v10, v230
	v_mul_lo_u32 v6, v6, s21
	v_cvt_pk_bf16_f32 v24, v26, s0
	v_cvt_pk_bf16_f32 v10, v10, s0
	v_add3_u32 v0, 0, v6, v0
	ds_write_b16 v31, v24 offset:4352
	ds_write_b16 v31, v10 offset:6528
	s_waitcnt lgkmcnt(0)
	s_barrier
; #define LAS __attribute__((address_space(3)))
; __device__ __forceinline__ unsigned pk_bf16(float lo, float hi) { const f32x2_t v = {lo, hi}; const bf16x2_t b = __builtin_convertvector(v, bf16x2_t); return __builtin_bit_cast(unsigned, b); }
; __device__ __forceinline__ float bf_lo(unsigned w) { return __uint_as_float(w << 16); }
; __device__ __forceinline__ float bf_hi(unsigned w) { return __uint_as_float(w & 0xffff0000u); }
; __device__ __forceinline__ void sgu_unit(int chunk, int g, const bf16_t* ZUV, const float* SS2, const float* gn, const bf16_t* SGUW, const float* bs, bf16_t* MIX, LAS unsigned char* lds) {
;     ...
;     f32x16 d0, d1;
; #pragma unroll
;     for (int r = 0; r < 16; ++r) { d0[r] = 0.f; d1[r] = 0.f; }
; #pragma unroll
;     for (int ks = 0; ks < 8; ++ks) {
;         const bf16x8 z0 = *(const LAS bf16x8*)(ZT + (32 * cb0 + q32) * 136 + 16 * ks + 8 * hi);
;         const bf16x8 z1 = *(const LAS bf16x8*)(ZT + (32 * (cb0 + 1) + q32) * 136 + 16 * ks + 8 * hi);
;         d0 = __builtin_amdgcn_mfma_f32_32x32x16_bf16(z0, wvv[ks], d0, 0, 0, 0);
;         d1 = __builtin_amdgcn_mfma_f32_32x32x16_bf16(z1, wvv[ks], d1, 0, 0, 0);
;     }
;     bf16_t* op = MIX + (size_t)(r0 + t) * DM + g * 128;
; #pragma unroll
;     for (int j = 0; j < 4; ++j) {
;         const int c0 = 32 * cb0 + 8 * j + 4 * hi, c1 = c0 + 32;
;         const u32x2 za = zav[j], zb = zbv[j];
;         u32x2 wa, wb;
;         wa.x = pk_bf16(bf_lo(za.x) * (d0[4 * j + 0] + bt), bf_hi(za.x) * (d0[4 * j + 1] + bt)); wa.y = pk_bf16(bf_lo(za.y) * (d0[4 * j + 2] + bt), bf_hi(za.y) * (d0[4 * j + 3] + bt));
;         wb.x = pk_bf16(bf_lo(zb.x) * (d1[4 * j + 0] + bt), bf_hi(zb.x) * (d1[4 * j + 1] + bt)); wb.y = pk_bf16(bf_lo(zb.y) * (d1[4 * j + 2] + bt), bf_hi(zb.y) * (d1[4 * j + 3] + bt));
;         *(u32x2*)(op + c0) = wa; *(u32x2*)(op + c1) = wb;
;     }
;     __syncthreads();
	ds_read_b128 v[6:9], v0 offset:8704
	ds_read_b128 v[10:13], v0
	ds_read_b128 v[82:85], v0 offset:32
	s_waitcnt lgkmcnt(1)
	v_mfma_f32_32x32x16_bf16 v[18:33], v[10:13], v[2:5], 0
	ds_read_b128 v[86:89], v0 offset:8736
	v_mfma_f32_32x32x16_bf16 v[2:17], v[6:9], v[2:5], 0
	s_waitcnt lgkmcnt(1)
	v_mfma_f32_32x32x16_bf16 v[18:33], v[82:85], v[58:61], v[18:33]
	s_waitcnt lgkmcnt(0)
	v_mfma_f32_32x32x16_bf16 v[2:17], v[86:89], v[58:61], v[2:17]
	ds_read_b128 v[58:61], v0 offset:64
	ds_read_b128 v[82:85], v0 offset:8768
	s_waitcnt lgkmcnt(1)
	v_mfma_f32_32x32x16_bf16 v[18:33], v[58:61], v[54:57], v[18:33]
	s_waitcnt lgkmcnt(0)
	v_mfma_f32_32x32x16_bf16 v[2:17], v[82:85], v[54:57], v[2:17]
	ds_read_b128 v[54:57], v0 offset:96
	ds_read_b128 v[58:61], v0 offset:8800
	s_waitcnt lgkmcnt(1)
	v_mfma_f32_32x32x16_bf16 v[18:33], v[54:57], v[50:53], v[18:33]
	s_waitcnt lgkmcnt(0)
	v_mfma_f32_32x32x16_bf16 v[2:17], v[58:61], v[50:53], v[2:17]
	ds_read_b128 v[50:53], v0 offset:128
	ds_read_b128 v[54:57], v0 offset:8832
	s_waitcnt lgkmcnt(1)
	v_mfma_f32_32x32x16_bf16 v[18:33], v[50:53], v[46:49], v[18:33]
	s_waitcnt lgkmcnt(0)
	v_mfma_f32_32x32x16_bf16 v[2:17], v[54:57], v[46:49], v[2:17]
	ds_read_b128 v[46:49], v0 offset:160
	ds_read_b128 v[50:53], v0 offset:8864
	s_waitcnt lgkmcnt(1)
	v_mfma_f32_32x32x16_bf16 v[18:33], v[46:49], v[42:45], v[18:33]
	s_waitcnt lgkmcnt(0)
	v_mfma_f32_32x32x16_bf16 v[2:17], v[50:53], v[42:45], v[2:17]
	ds_read_b128 v[42:45], v0 offset:192
	ds_read_b128 v[46:49], v0 offset:8896
	s_waitcnt lgkmcnt(1)
	v_mfma_f32_32x32x16_bf16 v[18:33], v[42:45], v[38:41], v[18:33]
	s_waitcnt lgkmcnt(0)
	v_mfma_f32_32x32x16_bf16 v[2:17], v[46:49], v[38:41], v[2:17]
	ds_read_b128 v[38:41], v0 offset:224
	ds_read_b128 v[42:45], v0 offset:8928
	s_waitcnt lgkmcnt(1)
	v_mfma_f32_32x32x16_bf16 v[18:33], v[38:41], v[34:37], v[18:33]
	v_lshlrev_b32_e32 v38, 16, v78
	v_and_b32_e32 v39, 0xffff0000, v78
	s_waitcnt lgkmcnt(0)
	v_mfma_f32_32x32x16_bf16 v[2:17], v[42:45], v[34:37], v[2:17]
	s_nop 7
	v_add_f32_e64 v18, v64, v18
	v_add_f32_e64 v19, v64, v19
	v_mul_f32_e64 v18, v18, v38
	v_mul_f32_e64 v19, v19, v39
	v_lshlrev_b32_e32 v38, 16, v79
	v_and_b32_e32 v39, 0xffff0000, v79
	v_pk_add_f32 v[20:21], v[64:65], v[20:21] op_sel_hi:[0,1]
	v_pk_mul_f32 v[20:21], v[20:21], v[38:39]
	v_lshlrev_b64 v[34:35], 11, v[80:81]
	v_cvt_pk_bf16_f32 v18, v18, v19
	v_cvt_pk_bf16_f32 v19, v20, v21
	v_lshlrev_b32_e32 v20, 16, v76
	v_and_b32_e32 v21, 0xffff0000, v76
	v_pk_add_f32 v[2:3], v[64:65], v[2:3] op_sel_hi:[0,1]
	v_lshl_add_u64 v[34:35], s[52:53], 0, v[34:35]
	v_lshl_or_b32 v36, v65, 2, s0
	v_pk_mul_f32 v[2:3], v[2:3], v[20:21]
	v_lshlrev_b32_e32 v20, 16, v77
	v_and_b32_e32 v21, 0xffff0000, v77
	v_pk_add_f32 v[4:5], v[64:65], v[4:5] op_sel_hi:[0,1]
	v_lshl_add_u64 v[34:35], v[34:35], 0, s[50:51]
	v_pk_mul_f32 v[4:5], v[4:5], v[20:21]
	v_ashrrev_i32_e32 v37, 31, v36
	v_cvt_pk_bf16_f32 v2, v2, v3
	v_cvt_pk_bf16_f32 v3, v4, v5
	v_lshl_add_u64 v[4:5], v[36:37], 1, v[34:35]
	global_store_dwordx2 v[4:5], v[18:19], off
	global_store_dwordx2 v[4:5], v[2:3], off offset:64
	v_lshlrev_b32_e32 v2, 16, v74
	v_and_b32_e32 v3, 0xffff0000, v74
	v_pk_add_f32 v[18:19], v[64:65], v[22:23] op_sel_hi:[0,1]
	v_pk_mul_f32 v[2:3], v[18:19], v[2:3]
	v_lshlrev_b32_e32 v18, 16, v75
	v_and_b32_e32 v19, 0xffff0000, v75
	v_pk_add_f32 v[20:21], v[64:65], v[24:25] op_sel_hi:[0,1]
	v_pk_mul_f32 v[18:19], v[20:21], v[18:19]
	v_cvt_pk_bf16_f32 v2, v2, v3
	v_cvt_pk_bf16_f32 v3, v18, v19
	v_lshlrev_b32_e32 v18, 16, v72
	v_and_b32_e32 v19, 0xffff0000, v72
	v_pk_add_f32 v[6:7], v[64:65], v[6:7] op_sel_hi:[0,1]
	v_pk_mul_f32 v[6:7], v[6:7], v[18:19]
	v_lshlrev_b32_e32 v18, 16, v73
	v_and_b32_e32 v19, 0xffff0000, v73
	v_pk_add_f32 v[8:9], v[64:65], v[8:9] op_sel_hi:[0,1]
	v_pk_mul_f32 v[8:9], v[8:9], v[18:19]
	v_cvt_pk_bf16_f32 v6, v6, v7
	v_cvt_pk_bf16_f32 v7, v8, v9
	global_store_dwordx2 v[4:5], v[2:3], off offset:16
	global_store_dwordx2 v[4:5], v[6:7], off offset:80
	v_lshlrev_b32_e32 v2, 16, v70
	v_and_b32_e32 v3, 0xffff0000, v70
	v_pk_add_f32 v[6:7], v[64:65], v[26:27] op_sel_hi:[0,1]
	v_pk_mul_f32 v[2:3], v[6:7], v[2:3]
	v_lshlrev_b32_e32 v6, 16, v71
	v_and_b32_e32 v7, 0xffff0000, v71
	v_pk_add_f32 v[8:9], v[64:65], v[28:29] op_sel_hi:[0,1]
	v_pk_mul_f32 v[6:7], v[8:9], v[6:7]
	v_cvt_pk_bf16_f32 v2, v2, v3
	v_cvt_pk_bf16_f32 v3, v6, v7
	v_lshlrev_b32_e32 v6, 16, v68
	v_and_b32_e32 v7, 0xffff0000, v68
	v_pk_add_f32 v[8:9], v[64:65], v[10:11] op_sel_hi:[0,1]
	v_pk_mul_f32 v[6:7], v[8:9], v[6:7]
	v_lshlrev_b32_e32 v8, 16, v69
	v_and_b32_e32 v9, 0xffff0000, v69
	v_pk_add_f32 v[10:11], v[64:65], v[12:13] op_sel_hi:[0,1]
	v_pk_mul_f32 v[8:9], v[10:11], v[8:9]
	v_cvt_pk_bf16_f32 v6, v6, v7
	v_cvt_pk_bf16_f32 v7, v8, v9
	global_store_dwordx2 v[4:5], v[2:3], off offset:32
	global_store_dwordx2 v[4:5], v[6:7], off offset:96
	v_lshlrev_b32_e32 v2, 16, v66
	v_and_b32_e32 v3, 0xffff0000, v66
	v_pk_add_f32 v[6:7], v[64:65], v[30:31] op_sel_hi:[0,1]
	v_pk_mul_f32 v[2:3], v[6:7], v[2:3]
	v_lshlrev_b32_e32 v6, 16, v67
	v_and_b32_e32 v7, 0xffff0000, v67
	v_pk_add_f32 v[8:9], v[64:65], v[32:33] op_sel_hi:[0,1]
	v_pk_mul_f32 v[6:7], v[8:9], v[6:7]
	v_cvt_pk_bf16_f32 v2, v2, v3
	v_cvt_pk_bf16_f32 v3, v6, v7
	v_lshlrev_b32_e32 v6, 16, v62
	v_and_b32_e32 v7, 0xffff0000, v62
	v_pk_add_f32 v[8:9], v[64:65], v[14:15] op_sel_hi:[0,1]
	v_pk_mul_f32 v[6:7], v[8:9], v[6:7]
	v_lshlrev_b32_e32 v8, 16, v63
	v_and_b32_e32 v9, 0xffff0000, v63
	v_pk_add_f32 v[10:11], v[64:65], v[16:17] op_sel_hi:[0,1]
	v_pk_mul_f32 v[8:9], v[10:11], v[8:9]
	v_cvt_pk_bf16_f32 v6, v6, v7
	v_cvt_pk_bf16_f32 v7, v8, v9
	global_store_dwordx2 v[4:5], v[2:3], off offset:48
	global_store_dwordx2 v[4:5], v[6:7], off offset:112
	s_barrier
	s_cbranch_scc0 .LBB0_249
.LBB0_250:
	s_waitcnt vmcnt(0)
	v_readlane_b32 s0, v254, 14
	v_readlane_b32 s1, v254, 15
	s_andn2_b64 vcc, exec, s[0:1]
	v_readlane_b32 s6, v252, 8
	v_cndmask_b32_e64 v0, 0, 1, s[0:1]
	v_cmp_ne_u32_e64 s[4:5], 1, v0
	s_mov_b32 s7, s2
	s_cbranch_vccnz .LBB0_270
